# speedup vs baseline: 1.0799x; 1.0004x over previous
.LBB0_481:
	s_cmp_gt_i32 s34, 3
	s_cselect_b64 s[0:1], -1, 0
	s_cmp_lt_i32 s35, 3
	s_cselect_b64 s[4:5], -1, 0
	s_or_b64 s[0:1], s[0:1], s[4:5]
	s_and_b64 vcc, exec, s[0:1]
	s_cbranch_vccnz .LBB0_536
	v_lshrrev_b32_e32 v1, 6, v0
	s_nop 0
	v_readfirstlane_b32 s98, v1
	s_nop 3
	s_and_b32 s98, s98, 15
	s_cmp_lt_u32 s98, 4
	s_cbranch_scc1 .Lprio_skip_3
	s_setprio 1
.Lprio_skip_3:
	v_and_b32_e32 v1, 0x3ff, v0
	s_mov_b64 s[0:1], 0
	v_mov_b32_e32 v3, v1
	s_load_dword s3, s[92:93], 0xd8
	v_ashrrev_i32_e32 v107, 6, v3
	v_and_b32_e32 v102, 15, v3
	v_bfe_u32 v6, v3, 4, 2
	v_and_b32_e32 v10, 48, v3
	s_waitcnt lgkmcnt(0)
	s_and_b32 s0, s3, 7
	s_cmp_lg_u32 s0, 0
	s_cselect_b64 s[4:5], -1, 0
	s_cmp_lt_i32 s3, 8
	s_cselect_b64 s[6:7], -1, 0
	s_lshl_b32 s0, s2, 5
	s_and_b32 s61, s0, 0xe0
	s_movk_i32 s0, 0x4300
	v_mul_lo_u32 v2, v107, s0
	v_add_u32_e32 v5, 0, v2
	v_and_b32_e32 v2, 63, v3
	v_lshrrev_b32_e32 v3, 1, v3
	v_lshlrev_b32_e32 v4, 3, v6
	v_mov_b32_e32 v105, 0
	v_mul_u32_u24_e32 v7, 0x210, v102
	s_movk_i32 s0, 0x110
	v_and_b32_e32 v104, 24, v3
	s_or_b64 s[36:37], s[6:7], s[4:5]
	v_lshlrev_b32_e32 v106, 2, v6
	v_and_b32_e32 v6, 8, v4
	v_lshrrev_b32_e32 v200, 1, v102
	v_mul_u32_u24_e32 v200, 0x410, v200
	v_and_b32_e32 v201, 1, v102
	v_lshlrev_b32_e32 v201, 3, v201
	v_lshl_add_u32 v201, v10, 1, v201
	v_add3_u32 v137, v5, v200, v201
	v_mad_u32_u24 v7, v102, s0, v5
	v_lshlrev_b32_e32 v11, 3, v2
	v_lshlrev_b32_e32 v12, 2, v2
	v_lshl_add_u64 v[8:9], s[86:87], 0, v[104:105]
	s_mov_b64 s[4:5], 0x4c00200
	s_mov_b32 s1, 0
	s_lshr_b32 s33, s3, 3
	s_ashr_i32 s60, s2, 3
	v_lshlrev_b32_e32 v136, 6, v102
	v_mov_b32_e32 v103, v105
	v_lshl_add_u64 v[108:109], v[8:9], 0, s[4:5]
	s_mov_b32 s62, 0x2ac0000
	s_mov_b32 s63, 0x2ac4000
	v_lshlrev_b32_e32 v110, 1, v4
	s_mov_b64 s[38:39], 0x2a00000
	s_mov_b32 s64, 0x2a01000
	s_mov_b64 s[40:41], 0x2a80000
	s_mov_b32 s65, 0x2a80000
	s_mov_b32 s66, 0x2ac8000
	s_mov_b32 s67, 0x2acc000
	s_mov_b64 s[44:45], 0x4c00000
	v_lshlrev_b32_e32 v112, 1, v6
	s_mov_b64 s[46:47], 0x400
	v_lshlrev_b32_e32 v104, 2, v2
	v_add_u32_e32 v138, v7, v10
	v_lshl_add_u32 v139, v2, 4, v5
	v_mov_b32_e32 v202, 0x3dd2d3e8
	v_mov_b32_e32 v203, 0x3dd2d3e8
	v_mov_b32_e32 v204, 0x40135761
	v_mov_b32_e32 v205, 0x40135761
	v_add_u32_e32 v140, v5, v12
	s_mov_b32 s68, 0
	s_branch .LBB0_484

.LBB0_496:
	s_cbranch_execz .LBB0_484
	v_readlane_b32 s34, v252, 16
	v_readlane_b32 s35, v252, 17
	s_setprio 0
	s_cmp_lt_i32 s35, 4
	s_cbranch_scc1 .LBB0_536
	s_waitcnt vmcnt(0)
	v_cmp_eq_u32_e32 vcc, 0, v1
	s_waitcnt vmcnt(0)
	s_barrier
	s_and_saveexec_b64 s[0:1], vcc
	s_cbranch_execz .LBB0_535
	s_cmp_lg_u32 s101, 0
	s_cbranch_scc1 .Lxl_glob_3
	s_and_b32 s6, s2, 7
	v_mov_b32_e32 v2, 0
	v_mov_b32_e32 v3, 1
	s_nop 3
	s_lshl_b32 s3, s6, 8
	s_add_u32 s4, s86, s3
	s_addc_u32 s5, s87, 0
	s_add_u32 s4, s4, 0x2b00498
	s_addc_u32 s5, s5, 0
	s_mov_b32 s98, 0
	global_atomic_add v2, v3, s[4:5]
